# adds: in the grid barrier the non-last XCD leaders poll the top arrival counter directly (TOP >= (gen+1)*nXCD) instead of waiting for the last leader's separate generation word, removing one fabric ro
# baseline (speedup 1.0000x reference)
; DI unsigned xb_ld(unsigned* p) { return __hip_atomic_load(p, __ATOMIC_RELAXED, __HIP_MEMORY_SCOPE_AGENT); }
; DI unsigned xb_add(unsigned* p, unsigned v) { return __hip_atomic_fetch_add(p, v, __ATOMIC_RELAXED, __HIP_MEMORY_SCOPE_AGENT); }
; #define XB_SPIN(cond, bar) do { unsigned _sp = 0; while (cond) { __builtin_amdgcn_s_sleep(1); \
;     if ((++_sp & 255u) == 0u) { if (xb_ld(&(bar)[XB_TMO])) break; if (_sp > XB_SPIN_CAP) { atomicAdd(&(bar)[XB_TMO], 1u); break; } } } } while (0)
; DI void xcd_barrier(unsigned* bar, volatile LAS unsigned* st) {
;     ...
;     if (old + 1u == (gen + 1u) * nloc) {
;       __builtin_amdgcn_fence(__ATOMIC_RELEASE, "agent");
;       asm volatile("s_waitcnt vmcnt(0)" ::: "memory");
;       const unsigned og = xb_add(&bar[XB_TOP], 1u);
;       const unsigned tg = og / nx;
;       if (og + 1u == (tg + 1u) * nx) xb_add(&bar[XB_TOPGEN], 1u);
;       else XB_SPIN(xb_ld(&bar[XB_TOPGEN]) == tg, bar);
.LBB0_363:
	s_andn2_saveexec_b64 s[0:1], s[0:1]
	s_cbranch_execz .LBB0_379
	v_mov_b32_e32 v2, s58
	v_add_co_u32_e32 v2, vcc, 0x22f23000, v2
	v_mov_b32_e32 v3, s59
	buffer_wbl2 sc1
	s_waitcnt vmcnt(0)
	v_addc_co_u32_e32 v3, vcc, 0, v3, vcc
	flat_atomic_add v2, v[2:3], v187 offset:1024 sc0
	v_cvt_f32_u32_e32 v3, v0
	v_sub_u32_e32 v4, 0, v0
	s_mov_b64 s[6:7], -1
	v_rcp_iflag_f32_e32 v3, v3
	s_nop 0
	v_mul_f32_e32 v3, 0x4f7ffffe, v3
	v_cvt_u32_f32_e32 v3, v3
	v_mul_lo_u32 v4, v4, v3
	v_mul_hi_u32 v4, v3, v4
	v_add_u32_e32 v3, v3, v4
	s_waitcnt vmcnt(0) lgkmcnt(0)
	v_mul_hi_u32 v3, v2, v3
	v_mul_lo_u32 v4, v3, v0
	v_sub_u32_e32 v4, v2, v4
	v_cmp_ge_u32_e32 vcc, v4, v0
	v_add_u32_e32 v5, 1, v3
	s_nop 0
	v_cndmask_b32_e32 v3, v3, v5, vcc
	v_sub_u32_e32 v5, v4, v0
	v_cndmask_b32_e32 v4, v4, v5, vcc
	v_cmp_ge_u32_e32 vcc, v4, v0
	v_add_u32_e32 v4, 1, v3
	v_add_u32_e32 v5, 1, v2
	v_cndmask_b32_e32 v4, v3, v4, vcc
	v_mad_u64_u32 v[2:3], s[0:1], v0, v4, v[0:1]
	v_mov_b32_e32 v6, v2
	s_add_u32 s0, s58, 0x22f23500
	s_addc_u32 s1, s59, 0
	v_cmp_ne_u32_e32 vcc, v5, v2
	v_mov_b64_e32 v[2:3], s[0:1]
	s_and_saveexec_b64 s[4:5], vcc
	s_cbranch_execz .LBB0_376
	v_mov_b64_e32 v[2:3], s[0:1]
	global_load_dword v0, v[2:3], off offset:-256 sc1
	s_mov_b64 s[10:11], 0
	s_waitcnt vmcnt(0) lgkmcnt(0)
	v_cmp_lt_u32_e32 vcc, v0, v6
	s_and_saveexec_b64 s[8:9], vcc
	s_cbranch_execz .LBB0_375
	s_add_u32 s6, s58, 0x22f20200
	s_addc_u32 s7, s59, 0
	s_mov_b32 s22, 1
	s_branch .LBB0_368

; DI unsigned xb_ld(unsigned* p) { return __hip_atomic_load(p, __ATOMIC_RELAXED, __HIP_MEMORY_SCOPE_AGENT); }
; #define XB_SPIN(cond, bar) do { unsigned _sp = 0; while (cond) { __builtin_amdgcn_s_sleep(1); \
;     if ((++_sp & 255u) == 0u) { if (xb_ld(&(bar)[XB_TMO])) break; if (_sp > XB_SPIN_CAP) { atomicAdd(&(bar)[XB_TMO], 1u); break; } } } } while (0)
; DI void xcd_barrier(unsigned* bar, volatile LAS unsigned* st) {
;     ...
;       else XB_SPIN(xb_ld(&bar[XB_TOPGEN]) == tg, bar);
.LBB0_373:
	v_mov_b64_e32 v[2:3], s[0:1]
	global_load_dword v0, v[2:3], off offset:-256 sc1
	s_add_i32 s22, s22, 1
	s_or_b64 s[16:17], s[16:17], exec
	s_waitcnt vmcnt(0) lgkmcnt(0)
	v_cmp_ge_u32_e32 vcc, v0, v6
	s_orn2_b64 s[14:15], vcc, exec
	s_branch .LBB0_367

; DI unsigned xb_ld(unsigned* p) { return __hip_atomic_load(p, __ATOMIC_RELAXED, __HIP_MEMORY_SCOPE_AGENT); }
; DI unsigned xb_add(unsigned* p, unsigned v) { return __hip_atomic_fetch_add(p, v, __ATOMIC_RELAXED, __HIP_MEMORY_SCOPE_AGENT); }
; #define XB_SPIN(cond, bar) do { unsigned _sp = 0; while (cond) { __builtin_amdgcn_s_sleep(1); \
;     if ((++_sp & 255u) == 0u) { if (xb_ld(&(bar)[XB_TMO])) break; if (_sp > XB_SPIN_CAP) { atomicAdd(&(bar)[XB_TMO], 1u); break; } } } } while (0)
; DI void xcd_barrier(unsigned* bar, volatile LAS unsigned* st) {
;     ...
;     if (old + 1u == (gen + 1u) * nloc) {
;       __builtin_amdgcn_fence(__ATOMIC_RELEASE, "agent");
;       asm volatile("s_waitcnt vmcnt(0)" ::: "memory");
;       const unsigned og = xb_add(&bar[XB_TOP], 1u);
;       const unsigned tg = og / nx;
;       if (og + 1u == (tg + 1u) * nx) xb_add(&bar[XB_TOPGEN], 1u);
;       else XB_SPIN(xb_ld(&bar[XB_TOPGEN]) == tg, bar);
.LBB0_861:
	s_andn2_saveexec_b64 s[0:1], s[0:1]
	s_cbranch_execz .LBB0_321
	v_mov_b32_e32 v2, s40
	v_add_co_u32_e32 v2, vcc, 0x22f23000, v2
	v_mov_b32_e32 v3, s41
	buffer_wbl2 sc1
	s_waitcnt vmcnt(0)
	v_addc_co_u32_e32 v3, vcc, 0, v3, vcc
	flat_atomic_add v2, v[2:3], v187 offset:1024 sc0
	v_cvt_f32_u32_e32 v3, v0
	v_sub_u32_e32 v4, 0, v0
	s_mov_b64 s[6:7], -1
	v_rcp_iflag_f32_e32 v3, v3
	s_nop 0
	v_mul_f32_e32 v3, 0x4f7ffffe, v3
	v_cvt_u32_f32_e32 v3, v3
	v_mul_lo_u32 v4, v4, v3
	v_mul_hi_u32 v4, v3, v4
	v_add_u32_e32 v3, v3, v4
	s_waitcnt vmcnt(0) lgkmcnt(0)
	v_mul_hi_u32 v3, v2, v3
	v_mul_lo_u32 v4, v3, v0
	v_sub_u32_e32 v4, v2, v4
	v_cmp_ge_u32_e32 vcc, v4, v0
	v_add_u32_e32 v5, 1, v3
	s_nop 0
	v_cndmask_b32_e32 v3, v3, v5, vcc
	v_sub_u32_e32 v5, v4, v0
	v_cndmask_b32_e32 v4, v4, v5, vcc
	v_cmp_ge_u32_e32 vcc, v4, v0
	v_add_u32_e32 v4, 1, v3
	v_add_u32_e32 v5, 1, v2
	v_cndmask_b32_e32 v4, v3, v4, vcc
	v_mad_u64_u32 v[2:3], s[0:1], v0, v4, v[0:1]
	v_mov_b32_e32 v6, v2
	s_add_u32 s0, s40, 0x22f23500
	s_addc_u32 s1, s41, 0
	v_cmp_ne_u32_e32 vcc, v5, v2
	v_mov_b64_e32 v[2:3], s[0:1]
	s_and_saveexec_b64 s[4:5], vcc
	s_cbranch_execz .LBB0_874
	v_mov_b64_e32 v[2:3], s[0:1]
	global_load_dword v0, v[2:3], off offset:-256 sc1
	s_mov_b64 s[10:11], 0
	s_waitcnt vmcnt(0) lgkmcnt(0)
	v_cmp_lt_u32_e32 vcc, v0, v6
	s_and_saveexec_b64 s[8:9], vcc
	s_cbranch_execz .LBB0_873
	s_add_u32 s6, s40, 0x22f20200
	s_addc_u32 s7, s41, 0
	s_mov_b32 s22, 1
	s_branch .LBB0_866
